# DSA attention unit: waves 4-7 staggered one segment behind waves 0-3 (3 barriers per tile, MFMA/VALU ping-pong) plus mask prefetch
# baseline (speedup 1.0000x reference)
.LBB0_939:
	s_lshl_b32 s0, s2, 8
	s_lshl_b32 s1, s28, 5
	v_and_b32_e32 v0, 31, v204
	s_add_i32 s4, s0, s1
	s_and_b32 s5, s29, 7
	v_ashrrev_i32_e32 v8, 5, v204
	v_or_b32_e32 v2, s4, v0
	v_mov_b64_e32 v[4:5], s[90:91]
	s_movk_i32 s0, 0x7200
	v_mad_i64_i32 v[4:5], s[0:1], v2, s0, v[4:5]
	s_lshl_b32 s58, s5, 8
	v_lshlrev_b32_e32 v6, 3, v8
	v_lshl_add_u64 v[4:5], v[4:5], 0, s[58:59]
	v_ashrrev_i32_e32 v7, 31, v6
	v_lshl_add_u64 v[4:5], v[6:7], 1, v[4:5]
	s_mov_b64 s[6:7], 0x25804800
	s_mov_b32 s1, 0x25804000
	s_lshl_b32 s0, s5, 7
	v_lshl_add_u64 v[6:7], v[4:5], 0, s[6:7]
	v_add_co_u32_e32 v4, vcc, s1, v4
	s_lshl_b32 s1, s5, 21
	s_barrier
	v_addc_co_u32_e32 v5, vcc, 0, v5, vcc
	global_load_dwordx4 v[98:101], v[6:7], off offset:32
	global_load_dwordx4 v[102:105], v[6:7], off offset:64
	global_load_dwordx4 v[106:109], v[6:7], off offset:96
	global_load_dwordx4 v[110:113], v[6:7], off offset:128
	global_load_dwordx4 v[114:117], v[6:7], off offset:160
	global_load_dwordx4 v[118:121], v[6:7], off offset:192
	global_load_dwordx4 v[122:125], v[4:5], off offset:2048
	global_load_dwordx4 v[126:129], v[6:7], off offset:224
	v_lshlrev_b32_e32 v4, 3, v204
	s_add_u32 s6, s90, s1
	v_ashrrev_i32_e32 v5, 31, v4
	s_addc_u32 s7, s91, 0
	v_lshl_add_u64 v[4:5], v[4:5], 1, s[6:7]
	s_mov_b64 s[6:7], 0x73500000
	v_lshl_add_u64 v[132:133], v[4:5], 0, s[6:7]
	s_mov_b64 s[6:7], 0x74500000
	v_lshl_add_u64 v[134:135], v[4:5], 0, s[6:7]
	s_lshl_b32 s6, s28, 1
	s_ashr_i32 s7, s6, 31
	s_lshl_b32 s1, s28, 11
	s_lshl_b64 s[8:9], s[6:7], 10
	s_add_i32 s1, s1, 0
	v_lshl_add_u64 v[4:5], v[132:133], 0, s[8:9]
	s_mov_b32 m0, s1
	v_ashrrev_i32_e32 v3, 31, v2
	global_load_lds_dwordx4 v[4:5], off
	v_lshl_add_u64 v[4:5], v[134:135], 0, s[8:9]
	s_or_b32 s8, s6, 1
	s_ashr_i32 s9, s8, 31
	s_lshl_b32 s5, s8, 10
	s_add_i32 m0, s1, 0x4000
	s_lshl_b64 s[10:11], s[8:9], 10
	s_add_i32 s5, s5, 0
	global_load_lds_dwordx4 v[4:5], off
	v_lshl_add_u64 v[4:5], v[132:133], 0, s[10:11]
	s_mov_b32 m0, s5
	v_lshlrev_b64 v[2:3], 10, v[2:3]
	global_load_lds_dwordx4 v[4:5], off
	v_lshl_add_u64 v[4:5], v[134:135], 0, s[10:11]
	s_add_i32 m0, s5, 0x4000
	s_lshl_b32 s2, s2, 2
	global_load_lds_dwordx4 v[4:5], off
	v_lshl_add_u64 v[2:3], s[90:91], 0, v[2:3]
	s_mov_b64 s[8:9], 0x72d00004
	s_lshl_b32 s3, s3, 2
	v_mov_b32_e32 v138, 0
	s_add_i32 s2, s2, 4
	v_lshl_add_u32 v131, v204, 4, 0
	v_lshlrev_b32_e32 v130, 2, v8
	v_lshl_add_u64 v[136:137], v[2:3], 0, s[8:9]
	s_add_i32 s6, s6, 17
	s_sub_i32 s3, 0, s3
	s_mov_b32 s5, 0x8000
	s_movk_i32 s8, 0xff80
	v_mov_b32_e32 v2, 0
	v_mov_b32_e32 v3, v138
	v_mov_b32_e32 v4, v138
	v_mov_b32_e32 v5, v138
	v_mov_b32_e32 v6, v138
	v_mov_b32_e32 v7, v138
	v_mov_b32_e32 v8, v138
	v_mov_b32_e32 v9, v138
	v_mov_b32_e32 v10, v138
	v_mov_b32_e32 v11, v138
	v_mov_b32_e32 v12, v138
	v_mov_b32_e32 v13, v138
	v_mov_b32_e32 v14, v138
	v_mov_b32_e32 v15, v138
	v_mov_b32_e32 v16, v138
	v_mov_b32_e32 v17, v138
	v_mov_b32_e32 v18, 0
	v_mov_b32_e32 v19, v138
	v_mov_b32_e32 v20, v138
	v_mov_b32_e32 v21, v138
	v_mov_b32_e32 v22, v138
	v_mov_b32_e32 v23, v138
	v_mov_b32_e32 v24, v138
	v_mov_b32_e32 v25, v138
	v_mov_b32_e32 v26, v138
	v_mov_b32_e32 v27, v138
	v_mov_b32_e32 v28, v138
	v_mov_b32_e32 v29, v138
	v_mov_b32_e32 v30, v138
	v_mov_b32_e32 v31, v138
	v_mov_b32_e32 v32, v138
	v_mov_b32_e32 v33, v138
	v_mov_b32_e32 v34, 0
	v_mov_b32_e32 v35, v138
	v_mov_b32_e32 v36, v138
	v_mov_b32_e32 v37, v138
	v_mov_b32_e32 v38, v138
	v_mov_b32_e32 v39, v138
	v_mov_b32_e32 v40, v138
	v_mov_b32_e32 v41, v138
	v_mov_b32_e32 v42, v138
	v_mov_b32_e32 v43, v138
	v_mov_b32_e32 v44, v138
	v_mov_b32_e32 v45, v138
	v_mov_b32_e32 v46, v138
	v_mov_b32_e32 v47, v138
	v_mov_b32_e32 v48, v138
	v_mov_b32_e32 v49, v138
	v_mov_b32_e32 v50, 0
	v_mov_b32_e32 v51, v138
	v_mov_b32_e32 v52, v138
	v_mov_b32_e32 v53, v138
	v_mov_b32_e32 v54, v138
	v_mov_b32_e32 v55, v138
	v_mov_b32_e32 v56, v138
	v_mov_b32_e32 v57, v138
	v_mov_b32_e32 v58, v138
	v_mov_b32_e32 v59, v138
	v_mov_b32_e32 v60, v138
	v_mov_b32_e32 v61, v138
	v_mov_b32_e32 v62, v138
	v_mov_b32_e32 v63, v138
	v_mov_b32_e32 v64, v138
	v_mov_b32_e32 v65, v138
	global_load_dwordx2 v[176:177], v[136:137], off offset:-4
	v_lshl_add_u64 v[136:137], v[136:137], 0, 8
	s_waitcnt vmcnt(0) lgkmcnt(0)
	s_barrier
	s_cmp_lt_u32 s28, 4
	s_cbranch_scc1 .Ldsa0_pre
	s_barrier
.Ldsa0_pre:
	s_branch .LBB0_941
.LBB0_940:
	s_add_i32 s7, s5, 0xffff8000
	s_and_b32 s7, s7, 0x8000
	v_add_u32_e32 v139, s7, v131
	ds_read_b128 v[66:69], v139
	ds_read_b128 v[82:85], v139 offset:1024
	s_add_i32 s6, s6, 16
	s_add_i32 s5, s5, 0x8000
	s_add_i32 s8, s8, 1
	s_waitcnt lgkmcnt(0)
	v_mfma_f32_32x32x16_bf16 v[66:81], v[66:69], v[122:125], 0
	v_mfma_f32_32x32x16_bf16 v[66:81], v[82:85], v[98:101], v[66:81]
	ds_read_b128 v[82:85], v139 offset:2048
	ds_read_b128 v[86:89], v139 offset:3072
	s_waitcnt lgkmcnt(0)
	v_mfma_f32_32x32x16_bf16 v[66:81], v[82:85], v[102:105], v[66:81]
	v_mfma_f32_32x32x16_bf16 v[66:81], v[86:89], v[106:109], v[66:81]
	ds_read_b128 v[82:85], v139 offset:4096
	ds_read_b128 v[86:89], v139 offset:5120
	s_waitcnt lgkmcnt(0)
	v_mfma_f32_32x32x16_bf16 v[66:81], v[82:85], v[110:113], v[66:81]
	v_mfma_f32_32x32x16_bf16 v[66:81], v[86:89], v[114:117], v[66:81]
	ds_read_b128 v[82:85], v139 offset:6144
	ds_read_b128 v[86:89], v139 offset:7168
	s_waitcnt lgkmcnt(0)
	v_mfma_f32_32x32x16_bf16 v[66:81], v[82:85], v[118:121], v[66:81]
	ds_read_b128 v[82:85], v139 offset:8192
	ds_read_b128 v[140:143], v139 offset:9216
	v_mfma_f32_32x32x16_bf16 v[66:81], v[86:89], v[126:129], v[66:81]
	s_waitcnt lgkmcnt(0)
	v_mfma_f32_32x32x16_bf16 v[82:97], v[82:85], v[122:125], 0
	s_nop 9
	v_min_f32_e32 v66, 0x42700000, v66
	v_exp_f32_e32 v66, v66
	v_min_f32_e32 v74, 0x42700000, v74
	v_min_f32_e32 v75, 0x42700000, v75
	v_mfma_f32_32x32x16_bf16 v[82:97], v[140:143], v[98:101], v[82:97]
	ds_read_b128 v[140:143], v139 offset:10240
	ds_read_b128 v[144:147], v139 offset:11264
	v_exp_f32_e32 v74, v74
	v_min_f32_e32 v76, 0x42700000, v76
	v_min_f32_e32 v77, 0x42700000, v77
	v_exp_f32_e32 v76, v76
	s_waitcnt lgkmcnt(0)
	v_mfma_f32_32x32x16_bf16 v[82:97], v[140:143], v[102:105], v[82:97]
	v_min_f32_e32 v78, 0x42700000, v78
	v_min_f32_e32 v79, 0x42700000, v79
	v_exp_f32_e32 v78, v78
	v_mfma_f32_32x32x16_bf16 v[82:97], v[144:147], v[106:109], v[82:97]
	ds_read_b128 v[140:143], v139 offset:12288
	ds_read_b128 v[144:147], v139 offset:13312
	v_min_f32_e32 v80, 0x42700000, v80
	v_min_f32_e32 v81, 0x42700000, v81
	v_exp_f32_e32 v80, v80
	s_waitcnt lgkmcnt(0)
	v_mfma_f32_32x32x16_bf16 v[82:97], v[140:143], v[110:113], v[82:97]
	v_mfma_f32_32x32x16_bf16 v[82:97], v[144:147], v[114:117], v[82:97]
	ds_read_b128 v[140:143], v139 offset:14336
	ds_read_b128 v[144:147], v139 offset:15360
	ds_read_b128 v[148:151], v139 offset:20480
	ds_read_b128 v[156:159], v139 offset:24576
	ds_read_b128 v[160:163], v139 offset:25600
	s_waitcnt lgkmcnt(0)
	v_mfma_f32_32x32x16_bf16 v[82:97], v[140:143], v[118:121], v[82:97]
	v_lshrrev_b32_e32 v140, v130, v176
	v_lshrrev_b32_e32 v141, v130, v177
	global_load_dwordx2 v[176:177], v[136:137], off offset:-4
	v_lshl_add_u64 v[136:137], v[136:137], 0, 8
	v_mfma_f32_32x32x16_bf16 v[82:97], v[144:147], v[126:129], v[82:97]
	s_barrier
	s_cmp_lt_u32 s28, 4
	s_cbranch_scc0 .Ldsa0_nodma
	s_add_i32 s7, s8, 0x80
	s_cmp_ge_u32 s7, s2
	s_cbranch_scc1 .Ldsa0_nodma
	s_add_i32 s10, s6, -17
	s_and_b32 s7, s5, 0x8000
	s_xor_b32 s7, s7, 0x8000
	s_ashr_i32 s11, s10, 31
	s_lshl_b64 s[10:11], s[10:11], 10
	s_add_i32 s9, s1, s7
	v_lshl_add_u64 v[178:179], v[132:133], 0, s[10:11]
	s_mov_b32 m0, s9
	s_nop 0
	global_load_lds_dwordx4 v[178:179], off
	v_lshl_add_u64 v[178:179], v[134:135], 0, s[10:11]
	s_add_i32 m0, s9, 0x4000
	s_add_i32 s10, s6, -16
	s_ashr_i32 s11, s10, 31
	s_lshl_b64 s[10:11], s[10:11], 10
	global_load_lds_dwordx4 v[178:179], off
	v_lshl_add_u64 v[178:179], v[132:133], 0, s[10:11]
	s_add_i32 m0, s9, 0x400
	s_nop 0
	global_load_lds_dwordx4 v[178:179], off
	v_lshl_add_u64 v[178:179], v[134:135], 0, s[10:11]
	s_add_i32 m0, s9, 0x4400
	s_nop 0
	global_load_lds_dwordx4 v[178:179], off
.Ldsa0_nodma:
	v_and_b32_e32 v142, 1, v140
	v_cmp_eq_u32_e32 vcc, 1, v142
	s_nop 1
	v_cndmask_b32_e32 v168, 0, v66, vcc
	v_and_b32_e32 v66, 1, v141
	s_nop 5
	v_min_f32_e32 v82, 0x42700000, v82
	v_exp_f32_e32 v82, v82
	v_cmp_eq_u32_e32 vcc, 1, v66
	v_min_f32_e32 v66, 0x42700000, v67
	v_exp_f32_e32 v66, v66
	v_cndmask_b32_e32 v169, 0, v82, vcc
	v_min_f32_e32 v67, 0x42700000, v83
	v_and_b32_e32 v82, 2, v140
	v_cmp_ne_u32_e32 vcc, 0, v82
	v_exp_f32_e32 v67, v67
	v_and_b32_e32 v83, 0x800, v140
	v_cndmask_b32_e32 v170, 0, v66, vcc
	v_and_b32_e32 v66, 2, v141
	v_cmp_ne_u32_e32 vcc, 0, v66
	v_min_f32_e32 v66, 0x42700000, v68
	v_exp_f32_e32 v66, v66
	v_cndmask_b32_e32 v171, 0, v67, vcc
	v_min_f32_e32 v67, 0x42700000, v84
	v_and_b32_e32 v68, 4, v140
	v_exp_f32_e32 v67, v67
	v_cmp_ne_u32_e32 vcc, 0, v68
	v_and_b32_e32 v68, 8, v140
	s_nop 0
	v_cndmask_b32_e32 v172, 0, v66, vcc
	v_and_b32_e32 v66, 4, v141
	v_cmp_ne_u32_e32 vcc, 0, v66
	v_min_f32_e32 v66, 0x42700000, v69
	v_cndmask_b32_e32 v173, 0, v67, vcc
	v_exp_f32_e32 v66, v66
	v_min_f32_e32 v67, 0x42700000, v85
	v_exp_f32_e32 v67, v67
	v_cmp_ne_u32_e32 vcc, 0, v68
	v_and_b32_e32 v85, 0x20000, v140
	s_nop 0
	v_cndmask_b32_e32 v174, 0, v66, vcc
	v_and_b32_e32 v66, 8, v141
	v_cmp_ne_u32_e32 vcc, 0, v66
	v_min_f32_e32 v66, 0x42700000, v70
	v_cndmask_b32_e32 v175, 0, v67, vcc
	v_min_f32_e32 v67, 0x42700000, v86
	v_exp_f32_e32 v68, v67
	v_min_f32_e32 v67, 0x42700000, v71
	v_exp_f32_e32 v66, v66
	v_exp_f32_e32 v69, v67
	v_min_f32_e32 v67, 0x42700000, v87
	v_exp_f32_e32 v70, v67
	v_and_b32_e32 v67, 0x100, v140
	v_and_b32_e32 v71, 0x200, v140
	v_cmp_ne_u32_e32 vcc, 0, v67
	v_and_b32_e32 v87, 0x80000, v140
	s_nop 0
	v_cndmask_b32_e32 v67, 0, v66, vcc
	v_cmp_ne_u32_e32 vcc, 0, v71
	v_and_b32_e32 v71, 0x200, v141
	s_nop 0
	v_cndmask_b32_e32 v66, 0, v69, vcc
	v_and_b32_e32 v69, 0x100, v141
	v_cmp_ne_u32_e32 vcc, 0, v69
	s_nop 1
	v_cndmask_b32_e32 v69, 0, v68, vcc
	v_cmp_ne_u32_e32 vcc, 0, v71
	v_min_f32_e32 v71, 0x42700000, v88
	v_cndmask_b32_e32 v68, 0, v70, vcc
	v_max_f32_e32 v70, v72, v72
	v_exp_f32_e32 v72, v71
	v_min_f32_e32 v71, 0x42700000, v73
	v_min_f32_e32 v70, 0x42700000, v70
	v_exp_f32_e32 v70, v70
	v_exp_f32_e32 v73, v71
	v_min_f32_e32 v71, 0x42700000, v89
	v_exp_f32_e32 v82, v71
	v_and_b32_e32 v71, 0x400, v140
	v_cmp_ne_u32_e32 vcc, 0, v71
	v_and_b32_e32 v89, 0x2000000, v140
	s_nop 0
	v_cndmask_b32_e32 v71, 0, v70, vcc
	v_cmp_ne_u32_e32 vcc, 0, v83
	v_and_b32_e32 v83, 0x800, v141
	s_nop 0
	v_cndmask_b32_e32 v70, 0, v73, vcc
	v_and_b32_e32 v73, 0x400, v141
	v_cmp_ne_u32_e32 vcc, 0, v73
	s_nop 1
	v_cndmask_b32_e32 v73, 0, v72, vcc
	v_cmp_ne_u32_e32 vcc, 0, v83
	v_exp_f32_e32 v83, v75
	v_min_f32_e32 v75, 0x42700000, v91
	v_cndmask_b32_e32 v72, 0, v82, vcc
	v_min_f32_e32 v82, 0x42700000, v90
	v_exp_f32_e32 v84, v75
	v_and_b32_e32 v75, 0x10000, v140
	v_exp_f32_e32 v82, v82
	v_cmp_ne_u32_e32 vcc, 0, v75
	v_and_b32_e32 v91, 0x8000000, v140
	v_pk_mov_b32 v[152:153], v[72:73], v[72:73] op_sel:[1,0]
	v_cndmask_b32_e32 v75, 0, v74, vcc
	v_cmp_ne_u32_e32 vcc, 0, v85
	v_and_b32_e32 v85, 0x20000, v141
	s_nop 0
	v_cndmask_b32_e32 v74, 0, v83, vcc
	v_and_b32_e32 v83, 0x10000, v141
	v_cmp_ne_u32_e32 vcc, 0, v83
	s_nop 1
	v_cndmask_b32_e32 v83, 0, v82, vcc
	v_cmp_ne_u32_e32 vcc, 0, v85
	v_exp_f32_e32 v85, v77
	v_min_f32_e32 v77, 0x42700000, v93
	v_cndmask_b32_e32 v82, 0, v84, vcc
	v_min_f32_e32 v84, 0x42700000, v92
	v_exp_f32_e32 v86, v77
	v_and_b32_e32 v77, 0x40000, v140
	v_exp_f32_e32 v84, v84
	v_cmp_ne_u32_e32 vcc, 0, v77
	v_pk_mov_b32 v[92:93], v[66:67], v[66:67] op_sel:[1,0]
	v_pk_add_f32 v[66:67], v[66:67], v[68:69]
	v_cndmask_b32_e32 v77, 0, v76, vcc
	v_cmp_ne_u32_e32 vcc, 0, v87
	v_and_b32_e32 v87, 0x80000, v141
	v_cvt_pk_bf16_f32 v92, v92, v93
	v_cndmask_b32_e32 v76, 0, v85, vcc
	v_and_b32_e32 v85, 0x40000, v141
	v_cmp_ne_u32_e32 vcc, 0, v85
	s_nop 1
	v_cndmask_b32_e32 v85, 0, v84, vcc
	v_cmp_ne_u32_e32 vcc, 0, v87
	v_exp_f32_e32 v87, v79
	v_min_f32_e32 v79, 0x42700000, v95
	v_cndmask_b32_e32 v84, 0, v86, vcc
	v_min_f32_e32 v86, 0x42700000, v94
	v_exp_f32_e32 v88, v79
	v_and_b32_e32 v79, 0x1000000, v140
	v_exp_f32_e32 v86, v86
	v_cmp_ne_u32_e32 vcc, 0, v79
	v_pk_mov_b32 v[94:95], v[70:71], v[70:71] op_sel:[1,0]
	s_nop 0
	v_cndmask_b32_e32 v79, 0, v78, vcc
	v_cmp_ne_u32_e32 vcc, 0, v89
	v_and_b32_e32 v89, 0x2000000, v141
	v_cvt_pk_bf16_f32 v93, v94, v95
	v_cndmask_b32_e32 v78, 0, v87, vcc
	v_and_b32_e32 v87, 0x1000000, v141
	v_cmp_ne_u32_e32 vcc, 0, v87
	v_pk_mov_b32 v[94:95], v[74:75], v[74:75] op_sel:[1,0]
	s_nop 0
	v_cndmask_b32_e32 v87, 0, v86, vcc
	v_cmp_ne_u32_e32 vcc, 0, v89
	v_exp_f32_e32 v89, v81
	v_min_f32_e32 v81, 0x42700000, v97
	v_cndmask_b32_e32 v86, 0, v88, vcc
	v_min_f32_e32 v88, 0x42700000, v96
	v_exp_f32_e32 v90, v81
	v_and_b32_e32 v81, 0x4000000, v140
	v_exp_f32_e32 v88, v88
	v_cmp_ne_u32_e32 vcc, 0, v81
	v_pk_mov_b32 v[96:97], v[76:77], v[76:77] op_sel:[1,0]
	v_cvt_pk_bf16_f32 v94, v94, v95
	v_cndmask_b32_e32 v81, 0, v80, vcc
	v_cmp_ne_u32_e32 vcc, 0, v91
	v_and_b32_e32 v91, 0x8000000, v141
	v_cvt_pk_bf16_f32 v95, v96, v97
	v_cndmask_b32_e32 v80, 0, v89, vcc
	v_and_b32_e32 v89, 0x4000000, v141
	v_cmp_ne_u32_e32 vcc, 0, v89
	s_cmp_lt_u32 s28, 4
	s_cbranch_scc1 .Ldsa0_b2
	s_waitcnt vmcnt(0)
.Ldsa0_b2:
	s_barrier
	ds_read_b128 v[140:143], v139 offset:16384
	v_pk_mov_b32 v[96:97], v[78:79], v[78:79] op_sel:[1,0]
	v_cndmask_b32_e32 v89, 0, v88, vcc
	v_cmp_ne_u32_e32 vcc, 0, v91
	v_cvt_pk_bf16_f32 v91, v172, v174
	v_pk_mov_b32 v[144:145], v[80:81], v[80:81] op_sel:[1,0]
	v_cndmask_b32_e32 v88, 0, v90, vcc
	v_cvt_pk_bf16_f32 v90, v168, v170
	v_cvt_pk_bf16_f32 v96, v96, v97
	v_cvt_pk_bf16_f32 v97, v144, v145
	ds_read_b128 v[144:147], v139 offset:17408
	s_waitcnt lgkmcnt(1)
	v_mfma_f32_32x32x16_bf16 v[2:17], v[90:93], v[140:143], v[2:17]
	v_pk_mov_b32 v[142:143], v[68:69], v[68:69] op_sel:[1,0]
	v_cvt_pk_bf16_f32 v140, v169, v171
	v_cvt_pk_bf16_f32 v142, v142, v143
	v_cvt_pk_bf16_f32 v143, v152, v153
	ds_read_b128 v[152:155], v139 offset:21504
	v_cvt_pk_bf16_f32 v141, v173, v175
	v_pk_add_f32 v[68:69], v[70:71], v[72:73]
	v_mfma_f32_32x32x16_bf16 v[2:17], v[94:97], v[148:151], v[2:17]
	v_pk_mov_b32 v[148:149], v[82:83], v[82:83] op_sel:[1,0]
	v_pk_mov_b32 v[150:151], v[84:85], v[84:85] op_sel:[1,0]
	v_cvt_pk_bf16_f32 v148, v148, v149
	v_cvt_pk_bf16_f32 v149, v150, v151
	v_pk_mov_b32 v[150:151], v[86:87], v[86:87] op_sel:[1,0]
	v_pk_add_f32 v[70:71], v[74:75], v[82:83]
	v_cvt_pk_bf16_f32 v150, v150, v151
	s_waitcnt lgkmcnt(1)
	v_mfma_f32_32x32x16_bf16 v[18:33], v[90:93], v[144:147], v[18:33]
	v_add_f32_e64 v74, v78, v86
	v_add_f32_e64 v75, v79, v87
	v_add_f32_e64 v72, v76, v84
	v_add_f32_e64 v73, v77, v85
	v_add_f32_e64 v76, v80, v88
	v_add_f32_e64 v77, v81, v89
	v_mfma_f32_32x32x16_bf16 v[2:17], v[140:143], v[156:159], v[2:17]
	v_pk_mov_b32 v[156:157], v[88:89], v[88:89] op_sel:[1,0]
	s_nop 0
	v_cvt_pk_bf16_f32 v151, v156, v157
	ds_read_b128 v[156:159], v139 offset:28672
	ds_read_b128 v[164:167], v139 offset:29696
	s_waitcnt lgkmcnt(2)
	v_mfma_f32_32x32x16_bf16 v[18:33], v[94:97], v[152:155], v[18:33]
	ds_read_b128 v[144:147], v139 offset:18432
	ds_read_b128 v[152:155], v139 offset:19456
	s_waitcnt lgkmcnt(1)
	v_mfma_f32_32x32x16_bf16 v[34:49], v[90:93], v[144:147], v[34:49]
	v_mfma_f32_32x32x16_bf16 v[2:17], v[148:151], v[156:159], v[2:17]
	ds_read_b128 v[144:147], v139 offset:22528
	ds_read_b128 v[156:159], v139 offset:23552
	s_waitcnt lgkmcnt(1)
	v_mfma_f32_32x32x16_bf16 v[34:49], v[94:97], v[144:147], v[34:49]
	v_mfma_f32_32x32x16_bf16 v[50:65], v[90:93], v[152:155], v[50:65]
	v_mfma_f32_32x32x16_bf16 v[18:33], v[140:143], v[160:163], v[18:33]
	ds_read_b128 v[144:147], v139 offset:26624
	ds_read_b128 v[160:163], v139 offset:27648
	s_waitcnt lgkmcnt(1)
	v_mfma_f32_32x32x16_bf16 v[34:49], v[140:143], v[144:147], v[34:49]
	v_mfma_f32_32x32x16_bf16 v[50:65], v[94:97], v[156:159], v[50:65]
	v_mfma_f32_32x32x16_bf16 v[18:33], v[148:151], v[164:167], v[18:33]
	ds_read_b128 v[144:147], v139 offset:30720
	ds_read_b128 v[164:167], v139 offset:31744
	v_add_f32_e32 v139, v168, v169
	v_add_f32_e32 v78, v138, v139
	s_waitcnt vmcnt(0) lgkmcnt(0)
	s_barrier
	v_mfma_f32_32x32x16_bf16 v[34:49], v[148:151], v[144:147], v[34:49]
	v_add_f32_e32 v144, v170, v171
	v_add_f32_e32 v145, v172, v173
	v_add_f32_e32 v78, v144, v78
	v_add_f32_e32 v146, v174, v175
	v_add_f32_e32 v78, v145, v78
	v_add_f32_e32 v78, v146, v78
	v_add_f32_e32 v67, v67, v78
	v_mfma_f32_32x32x16_bf16 v[50:65], v[140:143], v[160:163], v[50:65]
	v_add_f32_e32 v66, v66, v67
	v_add_f32_e32 v66, v69, v66
	v_add_f32_e32 v66, v68, v66
	v_add_f32_e32 v66, v71, v66
	v_add_f32_e32 v66, v70, v66
	v_add_f32_e32 v66, v73, v66
	v_add_f32_e32 v66, v72, v66
	v_mfma_f32_32x32x16_bf16 v[50:65], v[148:151], v[164:167], v[50:65]
	v_add_f32_e32 v66, v75, v66
	v_add_f32_e32 v66, v74, v66
	v_add_f32_e32 v66, v77, v66
	v_add_f32_e32 v138, v76, v66
	s_cmp_eq_u32 s3, s8
	s_cbranch_scc1 .LBB0_943
.LBB0_941:
	s_cmp_lt_u32 s28, 4
	s_cbranch_scc1 .LBB0_940
	s_add_i32 s7, s8, 0x81
	s_cmp_ge_u32 s7, s2
	s_cbranch_scc1 .LBB0_940
	s_add_i32 s10, s6, -1
	s_and_b32 s7, s5, 0x8000
	s_ashr_i32 s11, s10, 31
	s_lshl_b64 s[10:11], s[10:11], 10
	s_add_i32 s9, s1, s7
	v_lshl_add_u64 v[66:67], v[132:133], 0, s[10:11]
	s_mov_b32 m0, s9
	s_ashr_i32 s7, s6, 31
	global_load_lds_dwordx4 v[66:67], off
	v_lshl_add_u64 v[66:67], v[134:135], 0, s[10:11]
	s_add_i32 m0, s9, 0x4000
	s_lshl_b64 s[10:11], s[6:7], 10
	global_load_lds_dwordx4 v[66:67], off
	v_lshl_add_u64 v[66:67], v[132:133], 0, s[10:11]
	s_add_i32 m0, s9, 0x400
	s_nop 0
	global_load_lds_dwordx4 v[66:67], off
	v_lshl_add_u64 v[66:67], v[134:135], 0, s[10:11]
	s_add_i32 m0, s9, 0x4400
	s_nop 0
	global_load_lds_dwordx4 v[66:67], off
	s_branch .LBB0_940
.LBB0_943:
	s_cmp_lt_u32 s28, 4
	s_cbranch_scc0 .Ldsa0_post
	s_barrier

.LBB0_2560:
	s_sub_i32 s2, 31, s3
	s_lshl_b32 s0, s2, 8
	s_lshl_b32 s1, s28, 5
	v_and_b32_e32 v0, 31, v204
	s_add_i32 s4, s0, s1
	s_and_b32 s5, s29, 7
	v_ashrrev_i32_e32 v8, 5, v204
	v_or_b32_e32 v2, s4, v0
	v_mov_b64_e32 v[4:5], s[90:91]
	v_mad_i64_i32 v[4:5], s[0:1], v2, s41, v[4:5]
	s_lshl_b32 s58, s5, 8
	v_lshlrev_b32_e32 v6, 3, v8
	v_lshl_add_u64 v[4:5], v[4:5], 0, s[58:59]
	v_ashrrev_i32_e32 v7, 31, v6
	v_lshl_add_u64 v[4:5], v[6:7], 1, v[4:5]
	s_mov_b64 s[6:7], 0x25804800
	s_mov_b32 s1, 0x25804000
	s_lshl_b32 s0, s5, 7
	v_lshl_add_u64 v[6:7], v[4:5], 0, s[6:7]
	v_add_co_u32_e32 v4, vcc, s1, v4
	s_lshl_b32 s1, s5, 21
	s_barrier
	v_addc_co_u32_e32 v5, vcc, 0, v5, vcc
	global_load_dwordx4 v[98:101], v[6:7], off offset:32
	global_load_dwordx4 v[102:105], v[6:7], off offset:64
	global_load_dwordx4 v[106:109], v[6:7], off offset:96
	global_load_dwordx4 v[110:113], v[6:7], off offset:128
	global_load_dwordx4 v[114:117], v[6:7], off offset:160
	global_load_dwordx4 v[118:121], v[6:7], off offset:192
	global_load_dwordx4 v[122:125], v[4:5], off offset:2048
	global_load_dwordx4 v[126:129], v[6:7], off offset:224
	v_lshlrev_b32_e32 v4, 3, v204
	s_add_u32 s6, s90, s1
	v_ashrrev_i32_e32 v5, 31, v4
	s_addc_u32 s7, s91, 0
	v_lshl_add_u64 v[4:5], v[4:5], 1, s[6:7]
	s_mov_b64 s[6:7], 0x73500000
	v_lshl_add_u64 v[132:133], v[4:5], 0, s[6:7]
	s_mov_b64 s[6:7], 0x74500000
	v_lshl_add_u64 v[134:135], v[4:5], 0, s[6:7]
	s_lshl_b32 s6, s28, 1
	s_ashr_i32 s7, s6, 31
	s_lshl_b32 s1, s28, 11
	s_lshl_b64 s[8:9], s[6:7], 10
	s_add_i32 s1, s1, 0
	v_lshl_add_u64 v[4:5], v[132:133], 0, s[8:9]
	s_mov_b32 m0, s1
	v_ashrrev_i32_e32 v3, 31, v2
	global_load_lds_dwordx4 v[4:5], off
	v_lshl_add_u64 v[4:5], v[134:135], 0, s[8:9]
	s_or_b32 s8, s6, 1
	s_ashr_i32 s9, s8, 31
	s_lshl_b32 s5, s8, 10
	s_add_i32 m0, s1, 0x4000
	s_lshl_b64 s[10:11], s[8:9], 10
	s_add_i32 s5, s5, 0
	global_load_lds_dwordx4 v[4:5], off
	v_lshl_add_u64 v[4:5], v[132:133], 0, s[10:11]
	s_mov_b32 m0, s5
	v_lshlrev_b64 v[2:3], 10, v[2:3]
	global_load_lds_dwordx4 v[4:5], off
	v_lshl_add_u64 v[4:5], v[134:135], 0, s[10:11]
	s_add_i32 m0, s5, 0x4000
	s_lshl_b32 s2, s2, 2
	global_load_lds_dwordx4 v[4:5], off
	v_lshl_add_u64 v[2:3], s[90:91], 0, v[2:3]
	s_mov_b64 s[8:9], 0x72d00004
	s_lshl_b32 s3, s3, 2
	v_mov_b32_e32 v138, 0
	s_add_i32 s2, s2, 4
	v_lshl_add_u32 v131, v204, 4, 0
	v_lshlrev_b32_e32 v130, 2, v8
	v_lshl_add_u64 v[136:137], v[2:3], 0, s[8:9]
	s_add_i32 s6, s6, 17
	s_sub_i32 s3, 0, s3
	s_mov_b32 s5, 0x8000
	s_movk_i32 s8, 0xff80
	v_mov_b32_e32 v2, 0
	v_mov_b32_e32 v3, v138
	v_mov_b32_e32 v4, v138
	v_mov_b32_e32 v5, v138
	v_mov_b32_e32 v6, v138
	v_mov_b32_e32 v7, v138
	v_mov_b32_e32 v8, v138
	v_mov_b32_e32 v9, v138
	v_mov_b32_e32 v10, v138
	v_mov_b32_e32 v11, v138
	v_mov_b32_e32 v12, v138
	v_mov_b32_e32 v13, v138
	v_mov_b32_e32 v14, v138
	v_mov_b32_e32 v15, v138
	v_mov_b32_e32 v16, v138
	v_mov_b32_e32 v17, v138
	v_mov_b32_e32 v18, 0
	v_mov_b32_e32 v19, v138
	v_mov_b32_e32 v20, v138
	v_mov_b32_e32 v21, v138
	v_mov_b32_e32 v22, v138
	v_mov_b32_e32 v23, v138
	v_mov_b32_e32 v24, v138
	v_mov_b32_e32 v25, v138
	v_mov_b32_e32 v26, v138
	v_mov_b32_e32 v27, v138
	v_mov_b32_e32 v28, v138
	v_mov_b32_e32 v29, v138
	v_mov_b32_e32 v30, v138
	v_mov_b32_e32 v31, v138
	v_mov_b32_e32 v32, v138
	v_mov_b32_e32 v33, v138
	v_mov_b32_e32 v34, 0
	v_mov_b32_e32 v35, v138
	v_mov_b32_e32 v36, v138
	v_mov_b32_e32 v37, v138
	v_mov_b32_e32 v38, v138
	v_mov_b32_e32 v39, v138
	v_mov_b32_e32 v40, v138
	v_mov_b32_e32 v41, v138
	v_mov_b32_e32 v42, v138
	v_mov_b32_e32 v43, v138
	v_mov_b32_e32 v44, v138
	v_mov_b32_e32 v45, v138
	v_mov_b32_e32 v46, v138
	v_mov_b32_e32 v47, v138
	v_mov_b32_e32 v48, v138
	v_mov_b32_e32 v49, v138
	v_mov_b32_e32 v50, 0
	v_mov_b32_e32 v51, v138
	v_mov_b32_e32 v52, v138
	v_mov_b32_e32 v53, v138
	v_mov_b32_e32 v54, v138
	v_mov_b32_e32 v55, v138
	v_mov_b32_e32 v56, v138
	v_mov_b32_e32 v57, v138
	v_mov_b32_e32 v58, v138
	v_mov_b32_e32 v59, v138
	v_mov_b32_e32 v60, v138
	v_mov_b32_e32 v61, v138
	v_mov_b32_e32 v62, v138
	v_mov_b32_e32 v63, v138
	v_mov_b32_e32 v64, v138
	v_mov_b32_e32 v65, v138
	global_load_dwordx2 v[176:177], v[136:137], off offset:-4
	v_lshl_add_u64 v[136:137], v[136:137], 0, 8
	s_waitcnt vmcnt(0) lgkmcnt(0)
	s_barrier
	s_cmp_lt_u32 s28, 4
	s_cbranch_scc1 .Ldsa1_pre
	s_barrier
